# attn tile loop hand-rewritten: max folded into QK acc init, permlane max, saddr LDS-DMA interleaved in QK, 6-deep frag ring
# speedup vs baseline: 1.0400x; 1.0400x over previous
; #define LAS __attribute__((address_space(3)))
; #define LGK(n, f) asm volatile("s_waitcnt lgkmcnt(%1)" : "+v"(f) : "n"(n))
; __device__ __forceinline__ void attn_phase(int wv, const bf16_t* Q, const bf16_t* Kf, const bf16_t* Vt, const bf16_t* proj, bf16_t* mixed, LAS unsigned char* lds) { LIDS
;     ...
;             const int qb = half == 0 ? 63 - pi : pi;
;             const int q0 = qb * 256, qw0 = q0 + 32 * wid, q = qw0 + r, nt = 4 * qb + 4;
;             const char* kbase = (const char*)Kf + head * 192 * 2; const char* vbase = (const char*)Vt + (size_t)head * 128 * SEQ * 2;
;             bf16x8 qf[12];
; #pragma unroll
;             for (int ks = 0; ks < 12; ++ks) qf[ks] = *(const bf16x8*)(Q + (size_t)q * NQ + head * 192 + ks * 16 + h * 8);
;             float zf = 0.f; asm volatile("" : "+v"(zf));
;             f32x16 o[4];
; #pragma unroll
;             for (int b = 0; b < 4; ++b)
; #pragma unroll
;                 for (int j = 0; j < 16; ++j) o[b][j] = zf;
;             float mrun = -1e30f, lsum = 0.f;
;             asm volatile("" ::: "memory"); __builtin_amdgcn_s_barrier(); asm volatile("" ::: "memory");
;             ATT_ISSUE(0, 0);
;             for (int t = 0; t < nt; ++t) {
;                 const int b = t & 1;
;                 asm volatile("s_waitcnt vmcnt(0)" ::: "memory"); __builtin_amdgcn_s_barrier(); asm volatile("" ::: "memory");
;                 if (t + 1 < nt) ATT_ISSUE(t + 1, b ^ 1);
;                 if (64 * t <= qw0 + 31) {
;                     LAS unsigned char* kb_ = lds + b * ATT_STAGE; LAS unsigned char* vb_ = kb_ + ATT_KB;
;                     f32x16 s[2];
; #pragma unroll
;                     for (int kb = 0; kb < 2; ++kb)
; #pragma unroll
;                         for (int j = 0; j < 16; ++j) s[kb][j] = zf;
;                     unsigned kad[4];
; #pragma unroll
;                     for (int kl = 0; kl < 4; ++kl) kad[kl] = (unsigned)(size_t)kb_ + (unsigned)koffl[kl];
;                     bf16x8 fr_[4];
;     ...
;                     ATT_KRD(0); ATT_KRD(1); ATT_KRD(2); ATT_KRD(3);
; #pragma unroll
;                     for (int i = 0; i < 24; ++i) {
;                         LGK(i < 21 ? 3 : 23 - i, fr_[i & 3]);
;                         s[i & 1] = __builtin_amdgcn_mfma_f32_32x32x16_bf16(fr_[i & 3], qf[i >> 1], s[i & 1], 0, 0, 0);
;                         if (i + 4 < 24) ATT_KRD(i + 4);
;                     }
.LBB0_98:
	s_and_b64 s[16:17], s[68:69], exec
	s_cselect_b32 s17, s78, s59
	s_lshl_b32 s16, s17, 8
	s_add_i32 s16, s16, s56
	v_or_b32_e32 v223, s16, v206
	v_mad_i64_i32 v[0:1], s[18:19], v223, s27, v[204:205]
	global_load_dwordx4 v[112:115], v[0:1], off
	global_load_dwordx4 v[116:119], v[0:1], off offset:32
	global_load_dwordx4 v[120:123], v[0:1], off offset:64
	global_load_dwordx4 v[124:127], v[0:1], off offset:96
	global_load_dwordx4 v[128:131], v[0:1], off offset:128
	global_load_dwordx4 v[132:135], v[0:1], off offset:160
	global_load_dwordx4 v[136:139], v[0:1], off offset:192
	global_load_dwordx4 v[140:143], v[0:1], off offset:224
	global_load_dwordx4 v[144:147], v[0:1], off offset:256
	global_load_dwordx4 v[148:151], v[0:1], off offset:288
	global_load_dwordx4 v[152:155], v[0:1], off offset:320
	global_load_dwordx4 v[156:159], v[0:1], off offset:352
	v_mov_b32_e32 v0, v177
	s_mov_b64 s[18:19], s[6:7]
	s_mov_b64 s[20:21], s[4:5]
	s_mov_b32 m0, s58
	s_barrier
	v_mov_b32_e32 v1, v0
	v_lshl_add_u64 v[2:3], s[20:21], 0, v[176:177]
	global_load_lds_dwordx4 v[2:3], off
	v_lshl_add_u64 v[2:3], s[20:21], 0, v[194:195]
	s_add_i32 m0, s58, 0x2000
	v_mov_b32_e32 v4, v0
	global_load_lds_dwordx4 v[2:3], off
	v_lshl_add_u64 v[2:3], s[20:21], 0, v[196:197]
	s_add_i32 m0, s58, 0x4000
	v_mov_b32_e32 v5, v0
	global_load_lds_dwordx4 v[2:3], off
	v_lshl_add_u64 v[2:3], s[18:19], 0, v[198:199]
	s_add_i32 m0, s58, 0x6000
	v_mov_b32_e32 v6, v0
	global_load_lds_dwordx4 v[2:3], off
	v_lshl_add_u64 v[2:3], s[18:19], 0, v[200:201]
	s_add_i32 m0, s58, 0x8000
	v_mov_b32_e32 v7, v0
	global_load_lds_dwordx4 v[2:3], off
	v_mov_b32_e32 v2, v0
	v_mov_b32_e32 v3, v0
	v_mov_b32_e32 v8, v0
	v_mov_b32_e32 v9, v0
	v_mov_b32_e32 v10, v0
	v_mov_b32_e32 v11, v0
	v_mov_b32_e32 v12, v0
	v_mov_b32_e32 v13, v0
	v_mov_b32_e32 v14, v0
	s_cmp_lt_i32 s17, 0
	v_mov_b32_e32 v15, v0
	s_cbranch_scc1 .LBB0_109
	s_lshl_b32 s17, s17, 2
	v_mov_b64_e32 v[62:63], v[14:15]
	v_mov_b64_e32 v[46:47], v[14:15]
	v_mov_b64_e32 v[30:31], v[14:15]
	v_mov_b64_e32 v[78:79], v[14:15]
	s_add_i32 s17, s17, 4
	s_or_b32 s18, s16, 31
	s_mov_b32 s19, 0
	v_mov_b32_e32 v224, 0
	v_mov_b32_e32 v225, 0xf149f2ca
	s_mov_b32 s20, 63
	s_mov_b64 s[62:63], s[12:13]
	s_mov_b64 s[72:73], s[10:11]
	v_mov_b64_e32 v[60:61], v[12:13]
	v_mov_b64_e32 v[58:59], v[10:11]
	v_mov_b64_e32 v[56:57], v[8:9]
	v_mov_b64_e32 v[54:55], v[6:7]
	v_mov_b64_e32 v[52:53], v[4:5]
	v_mov_b64_e32 v[50:51], v[2:3]
	v_mov_b64_e32 v[48:49], v[0:1]
	v_mov_b64_e32 v[44:45], v[12:13]
	v_mov_b64_e32 v[42:43], v[10:11]
	v_mov_b64_e32 v[40:41], v[8:9]
	v_mov_b64_e32 v[38:39], v[6:7]
	v_mov_b64_e32 v[36:37], v[4:5]
	v_mov_b64_e32 v[34:35], v[2:3]
	v_mov_b64_e32 v[32:33], v[0:1]
	v_mov_b64_e32 v[28:29], v[12:13]
	v_mov_b64_e32 v[26:27], v[10:11]
	v_mov_b64_e32 v[24:25], v[8:9]
	v_mov_b64_e32 v[22:23], v[6:7]
	v_mov_b64_e32 v[20:21], v[4:5]
	v_mov_b64_e32 v[18:19], v[2:3]
	v_mov_b64_e32 v[16:17], v[0:1]
	v_mov_b64_e32 v[76:77], v[12:13]
	v_mov_b64_e32 v[74:75], v[10:11]
	v_mov_b64_e32 v[72:73], v[8:9]
	v_mov_b64_e32 v[70:71], v[6:7]
	v_mov_b64_e32 v[68:69], v[4:5]
	v_mov_b64_e32 v[66:67], v[2:3]
	v_mov_b64_e32 v[64:65], v[0:1]
	v_mov_b32_e32 v188, v215
	s_waitcnt vmcnt(0)
	s_branch .LBB0_102
.LBB0_102:
	s_waitcnt vmcnt(0)
	s_barrier
	s_and_b32 s21, s19, 1
	s_add_i32 s19, s19, 1
	s_xor_b32 s26, s21, 1
	s_mul_i32 s26, s26, 0xa000
	s_add_i32 s26, s58, s26
	s_sub_i32 s22, s20, 63
	s_cmp_gt_i32 s22, s18
	s_cbranch_scc1 .Lat_idle
	s_mul_i32 s21, s21, 0xa000
	s_add_i32 s21, s21, 16
	v_add_u32_e32 v178, s21, v207
	v_add_u32_e32 v179, s21, v208
	v_add_u32_e32 v180, s21, v209
	v_add_u32_e32 v181, s21, v217
	s_addk_i32 s21, 0x6000
	ds_read_b128 v[160:163], v178 offset:0x0
	ds_read_b128 v[164:167], v178 offset:0x3000
	v_add_u32_e32 v182, s21, v218
	v_add_u32_e32 v183, s21, v219
	v_add_u32_e32 v184, s21, v220
	v_add_u32_e32 v185, s21, v221
	ds_read_b128 v[168:171], v179 offset:0x0
	ds_read_b128 v[172:175], v179 offset:0x3000
	ds_read_b128 v[228:231], v180 offset:0x0
	ds_read_b128 v[232:235], v180 offset:0x3000
	s_waitcnt lgkmcnt(5)
	v_mfma_f32_32x32x16_bf16 v[96:111], v[160:163], v[112:115], v[0:15]
	ds_read_b128 v[160:163], v181 offset:0x0
	s_waitcnt lgkmcnt(5)
	v_mfma_f32_32x32x16_bf16 v[80:95], v[164:167], v[112:115], v[0:15]
	ds_read_b128 v[164:167], v181 offset:0x3000
	s_waitcnt lgkmcnt(5)
	v_mfma_f32_32x32x16_bf16 v[96:111], v[168:171], v[116:119], v[96:111]
	ds_read_b128 v[168:171], v178 offset:0x80
	s_cmp_ge_i32 s19, s17
	s_cbranch_scc1 .Lat_nd1
	s_mov_b32 m0, s26
	s_nop 0
	global_load_lds_dwordx4 v176, s[62:63]
.Lat_nd1:
	s_waitcnt lgkmcnt(5)
	v_mfma_f32_32x32x16_bf16 v[80:95], v[172:175], v[116:119], v[80:95]
	ds_read_b128 v[172:175], v178 offset:0x3080
	s_waitcnt lgkmcnt(5)
	v_mfma_f32_32x32x16_bf16 v[96:111], v[228:231], v[120:123], v[96:111]
	ds_read_b128 v[228:231], v179 offset:0x80
	s_waitcnt lgkmcnt(5)
	v_mfma_f32_32x32x16_bf16 v[80:95], v[232:235], v[120:123], v[80:95]
	ds_read_b128 v[232:235], v179 offset:0x3080
	s_waitcnt lgkmcnt(5)
	v_mfma_f32_32x32x16_bf16 v[96:111], v[160:163], v[124:127], v[96:111]
	ds_read_b128 v[160:163], v180 offset:0x80
	s_cmp_ge_i32 s19, s17
	s_cbranch_scc1 .Lat_nd2
	s_add_i32 m0, s26, 0x2000
	s_nop 0
	global_load_lds_dwordx4 v194, s[62:63]
.Lat_nd2:
	s_waitcnt lgkmcnt(5)
	v_mfma_f32_32x32x16_bf16 v[80:95], v[164:167], v[124:127], v[80:95]
	ds_read_b128 v[164:167], v180 offset:0x3080
	s_waitcnt lgkmcnt(5)
	v_mfma_f32_32x32x16_bf16 v[96:111], v[168:171], v[128:131], v[96:111]
	ds_read_b128 v[168:171], v181 offset:0x80
	s_waitcnt lgkmcnt(5)
	v_mfma_f32_32x32x16_bf16 v[80:95], v[172:175], v[128:131], v[80:95]
	ds_read_b128 v[172:175], v181 offset:0x3080
	s_waitcnt lgkmcnt(5)
	v_mfma_f32_32x32x16_bf16 v[96:111], v[228:231], v[132:135], v[96:111]
	ds_read_b128 v[228:231], v178 offset:0x100
	s_cmp_ge_i32 s19, s17
	s_cbranch_scc1 .Lat_nd3
	s_add_i32 m0, s26, 0x4000
	s_nop 0
	global_load_lds_dwordx4 v196, s[62:63]
; #define LGK(n, f) asm volatile("s_waitcnt lgkmcnt(%1)" : "+v"(f) : "n"(n))
; #define ATT_KRD(i) DSR(fr_[(i) & 3], kad[((i) >> 1) & 3], ((i) & 1) * (32 * 384) + ((i) >> 3) * 128)
; #define ATT_VRD(j) DSR(fr_[(j) & 3], vad[(j) >> 2], ((j) & 3) * 4096)
; __device__ __forceinline__ void attn_phase(int wv, const bf16_t* Q, const bf16_t* Kf, const bf16_t* Vt, const bf16_t* proj, bf16_t* mixed, LAS unsigned char* lds) { LIDS
;     ...
;                     bf16x8 fr_[4];
;     ...
;                     ATT_KRD(0); ATT_KRD(1); ATT_KRD(2); ATT_KRD(3);
; #pragma unroll
;                     for (int i = 0; i < 24; ++i) {
;                         LGK(i < 21 ? 3 : 23 - i, fr_[i & 3]);
;                         s[i & 1] = __builtin_amdgcn_mfma_f32_32x32x16_bf16(fr_[i & 3], qf[i >> 1], s[i & 1], 0, 0, 0);
;                         if (i + 4 < 24) ATT_KRD(i + 4);
;                     }
;     ...
;                     unsigned vad[4];
; #pragma unroll
;                     for (int c = 0; c < 4; ++c) vad[c] = (unsigned)(size_t)vb_ + (unsigned)voffl[c];
;     ...
;                     ATT_VRD(0); ATT_VRD(1); ATT_VRD(2); ATT_VRD(3);
;                     if (64 * t + 63 > qw0) {
; #pragma unroll
;                         for (int kb = 0; kb < 2; ++kb)
; #pragma unroll
;                             for (int j = 0; j < 16; ++j) { const int key = 64 * t + 32 * kb + 16 * (j >> 3) + 8 * h + (j & 7); if (key > q) s[kb][j] = -1e30f; }
;                     }
;                     float mx = -1e30f;
; #pragma unroll
;                     for (int kb = 0; kb < 2; ++kb)
; #pragma unroll
;                         for (int j = 0; j < 16; ++j) mx = fmaxf(mx, s[kb][j]);
;                     mx = fmaxf(mx, __shfl_xor(mx, 32));
;                     if (__builtin_amdgcn_ballot_w64(mx > mrun + 8.0f) != 0ull) {
.Lat_nd3:
	s_waitcnt lgkmcnt(5)
	v_mfma_f32_32x32x16_bf16 v[80:95], v[232:235], v[132:135], v[80:95]
	ds_read_b128 v[232:235], v178 offset:0x3100
	s_waitcnt lgkmcnt(5)
	v_mfma_f32_32x32x16_bf16 v[96:111], v[160:163], v[136:139], v[96:111]
	ds_read_b128 v[160:163], v179 offset:0x100
	s_waitcnt lgkmcnt(5)
	v_mfma_f32_32x32x16_bf16 v[80:95], v[164:167], v[136:139], v[80:95]
	ds_read_b128 v[164:167], v179 offset:0x3100
	s_waitcnt lgkmcnt(5)
	v_mfma_f32_32x32x16_bf16 v[96:111], v[168:171], v[140:143], v[96:111]
	ds_read_b128 v[168:171], v180 offset:0x100
	s_cmp_ge_i32 s19, s17
	s_cbranch_scc1 .Lat_nd4
	s_add_i32 m0, s26, 0x6000
	s_nop 0
	global_load_lds_dwordx4 v198, s[72:73]
.Lat_nd4:
	s_waitcnt lgkmcnt(5)
	v_mfma_f32_32x32x16_bf16 v[80:95], v[172:175], v[140:143], v[80:95]
	ds_read_b128 v[172:175], v180 offset:0x3100
	s_waitcnt lgkmcnt(5)
	v_mfma_f32_32x32x16_bf16 v[96:111], v[228:231], v[144:147], v[96:111]
	ds_read_b128 v[228:231], v181 offset:0x100
	s_waitcnt lgkmcnt(5)
	v_mfma_f32_32x32x16_bf16 v[80:95], v[232:235], v[144:147], v[80:95]
	ds_read_b128 v[232:235], v181 offset:0x3100
	s_waitcnt lgkmcnt(5)
	v_mfma_f32_32x32x16_bf16 v[96:111], v[160:163], v[148:151], v[96:111]
	ds_read_b128 v[160:163], v182 offset:0x0
	s_cmp_ge_i32 s19, s17
	s_cbranch_scc1 .Lat_nd5
	s_add_i32 m0, s26, 0x8000
	s_nop 0
	global_load_lds_dwordx4 v200, s[72:73]
.Lat_nd5:
	s_waitcnt lgkmcnt(5)
	v_mfma_f32_32x32x16_bf16 v[80:95], v[164:167], v[148:151], v[80:95]
	ds_read_b128 v[164:167], v182 offset:0x1000
	s_waitcnt lgkmcnt(5)
	v_mfma_f32_32x32x16_bf16 v[96:111], v[168:171], v[152:155], v[96:111]
	ds_read_b128 v[168:171], v182 offset:0x2000
	s_waitcnt lgkmcnt(5)
	v_mfma_f32_32x32x16_bf16 v[80:95], v[172:175], v[152:155], v[80:95]
	ds_read_b128 v[172:175], v182 offset:0x3000
	s_waitcnt lgkmcnt(5)
	v_mfma_f32_32x32x16_bf16 v[96:111], v[228:231], v[156:159], v[96:111]
	ds_read_b128 v[228:231], v183 offset:0x0
	s_waitcnt lgkmcnt(5)
	v_mfma_f32_32x32x16_bf16 v[80:95], v[232:235], v[156:159], v[80:95]
	ds_read_b128 v[232:235], v183 offset:0x1000
	s_cmp_le_i32 s20, s16
	s_nop 10
	s_cbranch_scc1 .Lat_nomask
	v_add_u32_e32 v186, s22, v222
	v_sub_u32_e32 v186, v223, v186
	v_cmp_le_i32_e32 vcc, 0, v186
	s_nop 1
	v_cndmask_b32_e32 v96, v215, v96, vcc
	v_cmp_le_i32_e32 vcc, 1, v186
	s_nop 1
	v_cndmask_b32_e32 v97, v215, v97, vcc
	v_cmp_le_i32_e32 vcc, 2, v186
	s_nop 1
	v_cndmask_b32_e32 v98, v215, v98, vcc
	v_cmp_le_i32_e32 vcc, 3, v186
	s_nop 1
	v_cndmask_b32_e32 v99, v215, v99, vcc
	v_cmp_le_i32_e32 vcc, 4, v186
	s_nop 1
	v_cndmask_b32_e32 v100, v215, v100, vcc
	v_cmp_le_i32_e32 vcc, 5, v186
	s_nop 1
	v_cndmask_b32_e32 v101, v215, v101, vcc
	v_cmp_le_i32_e32 vcc, 6, v186
	s_nop 1
	v_cndmask_b32_e32 v102, v215, v102, vcc
	v_cmp_le_i32_e32 vcc, 7, v186
	s_nop 1
	v_cndmask_b32_e32 v103, v215, v103, vcc
	v_cmp_le_i32_e32 vcc, 16, v186
	s_nop 1
	v_cndmask_b32_e32 v104, v215, v104, vcc
	v_cmp_le_i32_e32 vcc, 17, v186
	s_nop 1
	v_cndmask_b32_e32 v105, v215, v105, vcc
	v_cmp_le_i32_e32 vcc, 18, v186
	s_nop 1
	v_cndmask_b32_e32 v106, v215, v106, vcc
	v_cmp_le_i32_e32 vcc, 19, v186
	s_nop 1
	v_cndmask_b32_e32 v107, v215, v107, vcc
	v_cmp_le_i32_e32 vcc, 20, v186
	s_nop 1
	v_cndmask_b32_e32 v108, v215, v108, vcc
	v_cmp_le_i32_e32 vcc, 21, v186
	s_nop 1
	v_cndmask_b32_e32 v109, v215, v109, vcc
	v_cmp_le_i32_e32 vcc, 22, v186
	s_nop 1
	v_cndmask_b32_e32 v110, v215, v110, vcc
	v_cmp_le_i32_e32 vcc, 23, v186
	s_nop 1
	v_cndmask_b32_e32 v111, v215, v111, vcc
	v_cmp_le_i32_e32 vcc, 32, v186
	s_nop 1
	v_cndmask_b32_e32 v80, v215, v80, vcc
	v_cmp_le_i32_e32 vcc, 33, v186
	s_nop 1
	v_cndmask_b32_e32 v81, v215, v81, vcc
	v_cmp_le_i32_e32 vcc, 34, v186
	s_nop 1
	v_cndmask_b32_e32 v82, v215, v82, vcc
	v_cmp_le_i32_e32 vcc, 35, v186
	s_nop 1
	v_cndmask_b32_e32 v83, v215, v83, vcc
	v_cmp_le_i32_e32 vcc, 36, v186
	s_nop 1
	v_cndmask_b32_e32 v84, v215, v84, vcc
	v_cmp_le_i32_e32 vcc, 37, v186
	s_nop 1
	v_cndmask_b32_e32 v85, v215, v85, vcc
	v_cmp_le_i32_e32 vcc, 38, v186
	s_nop 1
	v_cndmask_b32_e32 v86, v215, v86, vcc
	v_cmp_le_i32_e32 vcc, 39, v186
	s_nop 1
	v_cndmask_b32_e32 v87, v215, v87, vcc
	v_cmp_le_i32_e32 vcc, 48, v186
	s_nop 1
	v_cndmask_b32_e32 v88, v215, v88, vcc
	v_cmp_le_i32_e32 vcc, 49, v186
	s_nop 1
	v_cndmask_b32_e32 v89, v215, v89, vcc
	v_cmp_le_i32_e32 vcc, 50, v186
	s_nop 1
	v_cndmask_b32_e32 v90, v215, v90, vcc
	v_cmp_le_i32_e32 vcc, 51, v186
	s_nop 1
	v_cndmask_b32_e32 v91, v215, v91, vcc
	v_cmp_le_i32_e32 vcc, 52, v186
	s_nop 1
	v_cndmask_b32_e32 v92, v215, v92, vcc
	v_cmp_le_i32_e32 vcc, 53, v186
	s_nop 1
	v_cndmask_b32_e32 v93, v215, v93, vcc
	v_cmp_le_i32_e32 vcc, 54, v186
	s_nop 1
	v_cndmask_b32_e32 v94, v215, v94, vcc
	v_cmp_le_i32_e32 vcc, 55, v186
	s_nop 1
	v_cndmask_b32_e32 v95, v215, v95, vcc
.Lat_nomask:
	v_max3_f32 v226, v96, v97, v98
	v_max3_f32 v226, v226, v99, v100
	v_max3_f32 v226, v226, v101, v102
	v_max3_f32 v226, v226, v103, v104
	v_max3_f32 v226, v226, v105, v106
	v_max3_f32 v226, v226, v107, v108
	v_max3_f32 v226, v226, v109, v110
	v_max_f32_e32 v226, v226, v111
	v_max3_f32 v227, v80, v81, v82
	v_max3_f32 v227, v227, v83, v84
	v_max3_f32 v227, v227, v85, v86
	v_max3_f32 v227, v227, v87, v88
	v_max3_f32 v227, v227, v89, v90
	v_max3_f32 v227, v227, v91, v92
	v_max3_f32 v227, v227, v93, v94
	v_max_f32_e32 v227, v227, v95
	v_max_f32_e32 v226, v226, v227
	v_mov_b32_e32 v227, v226
	s_nop 1
	v_permlane32_swap_b32_e32 v226, v227
	v_max_f32_e32 v226, v226, v227
	v_cmp_gt_f32_e32 vcc, v226, v188
	s_cbranch_vccnz .Lat_rare
; __device__ __forceinline__ unsigned cvt_pk_bf16(float lo, float hi) { unsigned r; asm volatile("v_cvt_pk_bf16_f32 %0, %1, %2" : "=v"(r) : "v"(lo), "v"(hi)); return r; }
; __device__ __forceinline__ float fast_exp2(float x) { return __builtin_amdgcn_exp2f(x); }
; #define LGK(n, f) asm volatile("s_waitcnt lgkmcnt(%1)" : "+v"(f) : "n"(n))
; #define ATT_VRD(j) DSR(fr_[(j) & 3], vad[(j) >> 2], ((j) & 3) * 4096)
; __device__ __forceinline__ void attn_phase(int wv, const bf16_t* Q, const bf16_t* Kf, const bf16_t* Vt, const bf16_t* proj, bf16_t* mixed, LAS unsigned char* lds) { LIDS
;     ...
;                     float ps = 0.f;
; #pragma unroll
;                     for (int kb = 0; kb < 2; ++kb)
; #pragma unroll
;                         for (int j = 0; j < 16; ++j) { s[kb][j] = fast_exp2(s[kb][j] - mrun); ps += s[kb][j]; }
;                     lsum += ps;
; #pragma unroll
;                     for (int c = 0; c < 4; ++c) {
;                         const int kb = c >> 1, sx = c & 1;
;                         u32x4 pw;
; #pragma unroll
;                         for (int j = 0; j < 4; ++j) pw[j] = cvt_pk_bf16(s[kb][8 * sx + 2 * j], s[kb][8 * sx + 2 * j + 1]);
;                         const bf16x8 pf = __builtin_bit_cast(bf16x8, pw);
; #pragma unroll
;                         for (int bb = 0; bb < 4; ++bb) {
;                             const int j = c * 4 + bb;
;                             LGK(j < 13 ? 3 : 15 - j, fr_[j & 3]);
;                             o[bb] = __builtin_amdgcn_mfma_f32_32x32x16_bf16(fr_[j & 3], pf, o[bb], 0, 0, 0);
;                             if (j + 4 < 16) ATT_VRD(j + 4);
;                         }
;                     }
.Lat_sm:
	v_exp_f32_e32 v96, v96
	v_exp_f32_e32 v97, v97
	s_nop 0
	v_add_f32_e32 v237, v96, v97
	v_cvt_pk_bf16_f32 v96, v96, v97
	v_exp_f32_e32 v98, v98
	v_exp_f32_e32 v99, v99
	v_add_f32_e32 v237, v237, v98
	v_add_f32_e32 v237, v237, v99
	v_cvt_pk_bf16_f32 v97, v98, v99
	v_exp_f32_e32 v100, v100
	v_exp_f32_e32 v101, v101
	v_add_f32_e32 v237, v237, v100
	v_add_f32_e32 v237, v237, v101
	v_cvt_pk_bf16_f32 v98, v100, v101
	v_exp_f32_e32 v102, v102
	v_exp_f32_e32 v103, v103
	v_add_f32_e32 v237, v237, v102
	v_add_f32_e32 v237, v237, v103
	v_cvt_pk_bf16_f32 v99, v102, v103
	s_nop 0
	s_waitcnt lgkmcnt(5)
	v_mfma_f32_32x32x16_bf16 v[48:63], v[160:163], v[96:99], v[48:63]
	ds_read_b128 v[160:163], v183 offset:0x2000
	v_exp_f32_e32 v104, v104
	v_exp_f32_e32 v105, v105
	v_add_f32_e32 v237, v237, v104
	v_add_f32_e32 v237, v237, v105
	v_cvt_pk_bf16_f32 v100, v104, v105
	s_waitcnt lgkmcnt(5)
	v_mfma_f32_32x32x16_bf16 v[32:47], v[164:167], v[96:99], v[32:47]
	ds_read_b128 v[164:167], v183 offset:0x3000
	v_exp_f32_e32 v106, v106
	v_exp_f32_e32 v107, v107
	v_add_f32_e32 v237, v237, v106
	v_add_f32_e32 v237, v237, v107
	v_cvt_pk_bf16_f32 v101, v106, v107
	s_waitcnt lgkmcnt(5)
	v_mfma_f32_32x32x16_bf16 v[16:31], v[168:171], v[96:99], v[16:31]
	ds_read_b128 v[168:171], v184 offset:0x0
	v_exp_f32_e32 v108, v108
	v_exp_f32_e32 v109, v109
	v_add_f32_e32 v237, v237, v108
	v_add_f32_e32 v237, v237, v109
	v_cvt_pk_bf16_f32 v102, v108, v109
	s_waitcnt lgkmcnt(5)
	v_mfma_f32_32x32x16_bf16 v[64:79], v[172:175], v[96:99], v[64:79]
	ds_read_b128 v[172:175], v184 offset:0x1000
	v_exp_f32_e32 v110, v110
	v_exp_f32_e32 v111, v111
	v_add_f32_e32 v237, v237, v110
	v_add_f32_e32 v237, v237, v111
	v_cvt_pk_bf16_f32 v103, v110, v111
	s_nop 0
	s_waitcnt lgkmcnt(5)
	v_mfma_f32_32x32x16_bf16 v[48:63], v[228:231], v[100:103], v[48:63]
	ds_read_b128 v[228:231], v184 offset:0x2000
	v_exp_f32_e32 v80, v80
	v_exp_f32_e32 v81, v81
	v_add_f32_e32 v237, v237, v80
	v_add_f32_e32 v237, v237, v81
	v_cvt_pk_bf16_f32 v80, v80, v81
	s_waitcnt lgkmcnt(5)
	v_mfma_f32_32x32x16_bf16 v[32:47], v[232:235], v[100:103], v[32:47]
	ds_read_b128 v[232:235], v184 offset:0x3000
	v_exp_f32_e32 v82, v82
	v_exp_f32_e32 v83, v83
	v_add_f32_e32 v237, v237, v82
	v_add_f32_e32 v237, v237, v83
	v_cvt_pk_bf16_f32 v81, v82, v83
	s_waitcnt lgkmcnt(5)
	v_mfma_f32_32x32x16_bf16 v[16:31], v[160:163], v[100:103], v[16:31]
	ds_read_b128 v[160:163], v185 offset:0x0
	v_exp_f32_e32 v84, v84
	v_exp_f32_e32 v85, v85
	v_add_f32_e32 v237, v237, v84
	v_add_f32_e32 v237, v237, v85
	v_cvt_pk_bf16_f32 v82, v84, v85
	s_waitcnt lgkmcnt(5)
	v_mfma_f32_32x32x16_bf16 v[64:79], v[164:167], v[100:103], v[64:79]
	ds_read_b128 v[164:167], v185 offset:0x1000
	v_exp_f32_e32 v86, v86
	v_exp_f32_e32 v87, v87
	v_add_f32_e32 v237, v237, v86
	v_add_f32_e32 v237, v237, v87
	v_cvt_pk_bf16_f32 v83, v86, v87
	s_nop 0
	s_waitcnt lgkmcnt(5)
	v_mfma_f32_32x32x16_bf16 v[48:63], v[168:171], v[80:83], v[48:63]
	ds_read_b128 v[168:171], v185 offset:0x2000
	v_exp_f32_e32 v88, v88
	v_exp_f32_e32 v89, v89
	v_add_f32_e32 v237, v237, v88
	v_add_f32_e32 v237, v237, v89
	v_cvt_pk_bf16_f32 v84, v88, v89
	s_waitcnt lgkmcnt(5)
	v_mfma_f32_32x32x16_bf16 v[32:47], v[172:175], v[80:83], v[32:47]
	ds_read_b128 v[172:175], v185 offset:0x3000
	v_exp_f32_e32 v90, v90
	v_exp_f32_e32 v91, v91
	v_add_f32_e32 v237, v237, v90
	v_add_f32_e32 v237, v237, v91
	v_cvt_pk_bf16_f32 v85, v90, v91
	s_waitcnt lgkmcnt(5)
	v_mfma_f32_32x32x16_bf16 v[16:31], v[228:231], v[80:83], v[16:31]
	v_exp_f32_e32 v92, v92
	v_exp_f32_e32 v93, v93
	v_add_f32_e32 v237, v237, v92
	v_add_f32_e32 v237, v237, v93
	v_cvt_pk_bf16_f32 v86, v92, v93
	s_waitcnt lgkmcnt(4)
	v_mfma_f32_32x32x16_bf16 v[64:79], v[232:235], v[80:83], v[64:79]
	v_exp_f32_e32 v94, v94
	v_exp_f32_e32 v95, v95
	v_add_f32_e32 v237, v237, v94
	v_add_f32_e32 v237, v237, v95
	v_cvt_pk_bf16_f32 v87, v94, v95
	s_nop 0
	s_waitcnt lgkmcnt(3)
	v_mfma_f32_32x32x16_bf16 v[48:63], v[160:163], v[84:87], v[48:63]
	s_waitcnt lgkmcnt(2)
	v_mfma_f32_32x32x16_bf16 v[32:47], v[164:167], v[84:87], v[32:47]
	s_waitcnt lgkmcnt(1)
	v_mfma_f32_32x32x16_bf16 v[16:31], v[168:171], v[84:87], v[16:31]
	s_waitcnt lgkmcnt(0)
	v_mfma_f32_32x32x16_bf16 v[64:79], v[172:175], v[84:87], v[64:79]
	v_add_f32_e32 v224, v224, v237
; __device__ __forceinline__ float fast_exp2(float x) { return __builtin_amdgcn_exp2f(x); }
; __device__ __forceinline__ void attn_phase(int wv, const bf16_t* Q, const bf16_t* Kf, const bf16_t* Vt, const bf16_t* proj, bf16_t* mixed, LAS unsigned char* lds) { LIDS
;     ...
;             for (int t = 0; t < nt; ++t) {
;                 const int b = t & 1;
;                 asm volatile("s_waitcnt vmcnt(0)" ::: "memory"); __builtin_amdgcn_s_barrier(); asm volatile("" ::: "memory");
;                 if (t + 1 < nt) ATT_ISSUE(t + 1, b ^ 1);
;                 if (64 * t <= qw0 + 31) {
;     ...
;                     if (__builtin_amdgcn_ballot_w64(mx > mrun + 8.0f) != 0ull) {
;                         const float mnew = fmaxf(mrun, mx), alpha = fast_exp2(mrun - mnew); mrun = mnew;
;                         lsum *= alpha;
; #pragma unroll
;                         for (int bb = 0; bb < 4; ++bb)
; #pragma unroll
;                             for (int j = 0; j < 16; ++j) o[bb][j] *= alpha;
;                     }
.Lat_next:
	s_add_i32 s20, s20, 64
	s_add_u32 s72, s72, 0x80
	s_addc_u32 s73, s73, 0
	s_add_u32 s62, s62, 0x30000
	s_addc_u32 s63, s63, 0
	s_cmp_eq_u32 s17, s19
	s_cbranch_scc0 .LBB0_102
	s_branch .LBB0_96
.Lat_idle:
	s_cmp_ge_i32 s19, s17
	s_cbranch_scc1 .Lat_next
	s_mov_b32 m0, s26
	s_nop 0
	global_load_lds_dwordx4 v176, s[62:63]
	s_add_i32 m0, s26, 0x2000
	s_nop 0
	global_load_lds_dwordx4 v194, s[62:63]
	s_add_i32 m0, s26, 0x4000
	s_nop 0
	global_load_lds_dwordx4 v196, s[62:63]
	s_add_i32 m0, s26, 0x6000
	s_nop 0
	global_load_lds_dwordx4 v198, s[72:73]
	s_add_i32 m0, s26, 0x8000
	s_nop 0
	global_load_lds_dwordx4 v200, s[72:73]
	s_branch .Lat_next
.Lat_rare:
	v_sub_f32_e32 v186, v226, v0
	v_max_f32_e32 v227, v225, v186
	v_sub_f32_e32 v186, v225, v227
	v_exp_f32_e32 v186, v186
	v_add_f32_e32 v236, v227, v0
	v_mov_b32_e32 v225, v227
	v_mov_b32_e32 v188, 0x41000000
	v_sub_f32_e32 v96, v96, v236
	v_sub_f32_e32 v97, v97, v236
	v_sub_f32_e32 v98, v98, v236
	v_sub_f32_e32 v99, v99, v236
	v_sub_f32_e32 v100, v100, v236
	v_sub_f32_e32 v101, v101, v236
	v_sub_f32_e32 v102, v102, v236
	v_sub_f32_e32 v103, v103, v236
	v_sub_f32_e32 v104, v104, v236
	v_sub_f32_e32 v105, v105, v236
	v_sub_f32_e32 v106, v106, v236
	v_sub_f32_e32 v107, v107, v236
	v_sub_f32_e32 v108, v108, v236
	v_sub_f32_e32 v109, v109, v236
	v_sub_f32_e32 v110, v110, v236
	v_sub_f32_e32 v111, v111, v236
	v_sub_f32_e32 v80, v80, v236
	v_sub_f32_e32 v81, v81, v236
	v_sub_f32_e32 v82, v82, v236
	v_sub_f32_e32 v83, v83, v236
	v_sub_f32_e32 v84, v84, v236
	v_sub_f32_e32 v85, v85, v236
	v_sub_f32_e32 v86, v86, v236
	v_sub_f32_e32 v87, v87, v236
	v_sub_f32_e32 v88, v88, v236
	v_sub_f32_e32 v89, v89, v236
	v_sub_f32_e32 v90, v90, v236
	v_sub_f32_e32 v91, v91, v236
	v_sub_f32_e32 v92, v92, v236
	v_sub_f32_e32 v93, v93, v236
	v_sub_f32_e32 v94, v94, v236
	v_sub_f32_e32 v95, v95, v236
	v_sub_f32_e32 v0, 0, v227
	v_mov_b32_e32 v1, v0
	v_mov_b32_e32 v2, v0
	v_mov_b32_e32 v3, v0
	v_mov_b32_e32 v4, v0
	v_mov_b32_e32 v5, v0
	v_mov_b32_e32 v6, v0
	v_mov_b32_e32 v7, v0
	v_mov_b32_e32 v8, v0
	v_mov_b32_e32 v9, v0
	v_mov_b32_e32 v10, v0
	v_mov_b32_e32 v11, v0
	v_mov_b32_e32 v12, v0
	v_mov_b32_e32 v13, v0
	v_mov_b32_e32 v14, v0
	v_mov_b32_e32 v15, v0
	v_mul_f32_e32 v48, v186, v48
	v_mul_f32_e32 v49, v186, v49
	v_mul_f32_e32 v50, v186, v50
	v_mul_f32_e32 v51, v186, v51
	v_mul_f32_e32 v52, v186, v52
	v_mul_f32_e32 v53, v186, v53
	v_mul_f32_e32 v54, v186, v54
	v_mul_f32_e32 v55, v186, v55
	v_mul_f32_e32 v56, v186, v56
	v_mul_f32_e32 v57, v186, v57
	v_mul_f32_e32 v58, v186, v58
	v_mul_f32_e32 v59, v186, v59
	v_mul_f32_e32 v60, v186, v60
	v_mul_f32_e32 v61, v186, v61
	v_mul_f32_e32 v62, v186, v62
	v_mul_f32_e32 v63, v186, v63
	v_mul_f32_e32 v32, v186, v32
	v_mul_f32_e32 v33, v186, v33
	v_mul_f32_e32 v34, v186, v34
	v_mul_f32_e32 v35, v186, v35
	v_mul_f32_e32 v36, v186, v36
	v_mul_f32_e32 v37, v186, v37
	v_mul_f32_e32 v38, v186, v38
	v_mul_f32_e32 v39, v186, v39
	v_mul_f32_e32 v40, v186, v40
	v_mul_f32_e32 v41, v186, v41
	v_mul_f32_e32 v42, v186, v42
	v_mul_f32_e32 v43, v186, v43
	v_mul_f32_e32 v44, v186, v44
	v_mul_f32_e32 v45, v186, v45
	v_mul_f32_e32 v46, v186, v46
	v_mul_f32_e32 v47, v186, v47
	v_mul_f32_e32 v16, v186, v16
	v_mul_f32_e32 v17, v186, v17
	v_mul_f32_e32 v18, v186, v18
	v_mul_f32_e32 v19, v186, v19
	v_mul_f32_e32 v20, v186, v20
	v_mul_f32_e32 v21, v186, v21
	v_mul_f32_e32 v22, v186, v22
	v_mul_f32_e32 v23, v186, v23
	v_mul_f32_e32 v24, v186, v24
	v_mul_f32_e32 v25, v186, v25
	v_mul_f32_e32 v26, v186, v26
	v_mul_f32_e32 v27, v186, v27
	v_mul_f32_e32 v28, v186, v28
	v_mul_f32_e32 v29, v186, v29
	v_mul_f32_e32 v30, v186, v30
	v_mul_f32_e32 v31, v186, v31
	v_mul_f32_e32 v64, v186, v64
	v_mul_f32_e32 v65, v186, v65
	v_mul_f32_e32 v66, v186, v66
	v_mul_f32_e32 v67, v186, v67
	v_mul_f32_e32 v68, v186, v68
	v_mul_f32_e32 v69, v186, v69
	v_mul_f32_e32 v70, v186, v70
	v_mul_f32_e32 v71, v186, v71
	v_mul_f32_e32 v72, v186, v72
	v_mul_f32_e32 v73, v186, v73
	v_mul_f32_e32 v74, v186, v74
	v_mul_f32_e32 v75, v186, v75
	v_mul_f32_e32 v76, v186, v76
	v_mul_f32_e32 v77, v186, v77
	v_mul_f32_e32 v78, v186, v78
	v_mul_f32_e32 v79, v186, v79
	v_mul_f32_e32 v224, v186, v224
	s_branch .Lat_sm
